# v3 + phase C scan: prefetched loads 3 batches ahead, batched decay staging loads
# speedup vs baseline: 1.0020x; 1.0020x over previous
.LBB0_468:
	v_ashrrev_i32_e32 v14, 5, v4
	v_ashrrev_i32_e32 v15, 31, v14
	v_lshlrev_b64 v[10:11], 11, v[14:15]
	v_lshlrev_b32_e32 v0, 2, v5
	v_lshl_add_u64 v[10:11], s[8:9], 0, v[10:11]
	v_and_b32_e32 v0, 0x1f0, v0
	v_lshl_add_u64 v[10:11], v[10:11], 0, v[0:1]
	v_lshlrev_b32_e32 v28, 9, v14
	v_add3_u32 v28, 0, v28, v0
	global_load_dwordx4 v[32:35], v[10:11], off
	v_add_u32_e32 v10, 0x200, v4
	v_ashrrev_i32_e32 v14, 5, v10
	v_ashrrev_i32_e32 v15, 31, v14
	v_lshlrev_b64 v[10:11], 11, v[14:15]
	v_lshl_add_u64 v[10:11], s[8:9], 0, v[10:11]
	v_lshl_add_u64 v[10:11], v[10:11], 0, v[0:1]
	v_lshlrev_b32_e32 v29, 9, v14
	v_add3_u32 v29, 0, v29, v0
	global_load_dwordx4 v[36:39], v[10:11], off
	v_add_u32_e32 v10, 0x400, v4
	v_ashrrev_i32_e32 v14, 5, v10
	v_ashrrev_i32_e32 v15, 31, v14
	v_lshlrev_b64 v[10:11], 11, v[14:15]
	v_lshl_add_u64 v[10:11], s[8:9], 0, v[10:11]
	v_lshl_add_u64 v[10:11], v[10:11], 0, v[0:1]
	v_lshlrev_b32_e32 v30, 9, v14
	v_add3_u32 v30, 0, v30, v0
	global_load_dwordx4 v[40:43], v[10:11], off
	v_add_u32_e32 v10, 0x600, v4
	v_ashrrev_i32_e32 v14, 5, v10
	v_ashrrev_i32_e32 v15, 31, v14
	v_lshlrev_b64 v[10:11], 11, v[14:15]
	v_lshl_add_u64 v[10:11], s[8:9], 0, v[10:11]
	v_lshl_add_u64 v[10:11], v[10:11], 0, v[0:1]
	v_lshlrev_b32_e32 v31, 9, v14
	v_add3_u32 v31, 0, v31, v0
	global_load_dwordx4 v[44:47], v[10:11], off
	s_movk_i32 s10, 0x17ff
	v_cmp_lt_i32_e64 s[18:19], s10, v4
	v_add_u32_e32 v5, 0x2000, v5
	s_or_b64 s[20:21], s[18:19], s[20:21]
	v_add_u32_e32 v4, 0x800, v4
	s_waitcnt vmcnt(3)
	ds_write_b128 v28, v[32:35]
	s_waitcnt vmcnt(2)
	ds_write_b128 v29, v[36:39]
	s_waitcnt vmcnt(1)
	ds_write_b128 v30, v[40:43]
	s_waitcnt vmcnt(0)
	ds_write_b128 v31, v[44:47]
	s_andn2_b64 exec, exec, s[20:21]
	s_cbranch_execnz .LBB0_468

.LBB0_470:
	s_mov_b64 s[8:9], 0x800
	global_load_ushort v28, v[4:5], off offset:-1792
	global_load_ushort v29, v[4:5], off offset:-1536
	global_load_ushort v30, v[4:5], off offset:-1280
	global_load_ushort v31, v[4:5], off offset:-1024
	global_load_ushort v32, v[4:5], off offset:-768
	global_load_ushort v33, v[4:5], off offset:-512
	global_load_ushort v34, v[4:5], off offset:-256
	global_load_ushort v35, v[4:5], off
	v_lshl_add_u64 v[68:69], v[4:5], 0, s[8:9]
	global_load_ushort v36, v[68:69], off offset:-1792
	global_load_ushort v37, v[68:69], off offset:-1536
	global_load_ushort v38, v[68:69], off offset:-1280
	global_load_ushort v39, v[68:69], off offset:-1024
	global_load_ushort v40, v[68:69], off offset:-768
	global_load_ushort v41, v[68:69], off offset:-512
	global_load_ushort v42, v[68:69], off offset:-256
	global_load_ushort v43, v[68:69], off
	v_lshl_add_u64 v[68:69], v[68:69], 0, s[8:9]
	global_load_ushort v44, v[68:69], off offset:-1792
	global_load_ushort v45, v[68:69], off offset:-1536
	global_load_ushort v46, v[68:69], off offset:-1280
	global_load_ushort v47, v[68:69], off offset:-1024
	global_load_ushort v48, v[68:69], off offset:-768
	global_load_ushort v49, v[68:69], off offset:-512
	global_load_ushort v50, v[68:69], off offset:-256
	global_load_ushort v51, v[68:69], off
	v_lshl_add_u64 v[68:69], v[68:69], 0, s[8:9]
	global_load_ushort v52, v[68:69], off offset:-1792
	global_load_ushort v53, v[68:69], off offset:-1536
	global_load_ushort v54, v[68:69], off offset:-1280
	global_load_ushort v55, v[68:69], off offset:-1024
	global_load_ushort v56, v[68:69], off offset:-768
	global_load_ushort v57, v[68:69], off offset:-512
	global_load_ushort v58, v[68:69], off offset:-256
	global_load_ushort v59, v[68:69], off
	v_lshl_add_u64 v[68:69], v[68:69], 0, s[8:9]
	ds_read2st64_b32 v[12:13], v0 offset0:0 offset1:2
	ds_read2st64_b32 v[14:15], v0 offset0:4 offset1:6
	ds_read2st64_b32 v[16:17], v0 offset0:8 offset1:10
	ds_read2st64_b32 v[18:19], v0 offset0:12 offset1:14
	s_waitcnt vmcnt(24)
	v_lshlrev_b32_e32 v28, 16, v28
	v_lshlrev_b32_e32 v29, 16, v29
	v_lshlrev_b32_e32 v30, 16, v30
	v_lshlrev_b32_e32 v31, 16, v31
	v_lshlrev_b32_e32 v32, 16, v32
	v_lshlrev_b32_e32 v33, 16, v33
	v_lshlrev_b32_e32 v34, 16, v34
	v_lshlrev_b32_e32 v35, 16, v35
	s_waitcnt lgkmcnt(0)
	v_fmac_f32_e32 v28, v10, v12
	v_fmac_f32_e32 v29, v28, v13
	v_bfe_u32 v20, v28, 16, 1
	v_add3_u32 v20, v28, v20, s47
	global_store_short_d16_hi v[4:5], v20, off offset:-1792
	v_fmac_f32_e32 v30, v29, v14
	v_bfe_u32 v21, v29, 16, 1
	v_add3_u32 v21, v29, v21, s47
	global_store_short_d16_hi v[4:5], v21, off offset:-1536
	v_fmac_f32_e32 v31, v30, v15
	v_bfe_u32 v22, v30, 16, 1
	v_add3_u32 v22, v30, v22, s47
	global_store_short_d16_hi v[4:5], v22, off offset:-1280
	v_fmac_f32_e32 v32, v31, v16
	v_bfe_u32 v23, v31, 16, 1
	v_add3_u32 v23, v31, v23, s47
	global_store_short_d16_hi v[4:5], v23, off offset:-1024
	v_fmac_f32_e32 v33, v32, v17
	v_bfe_u32 v24, v32, 16, 1
	v_add3_u32 v24, v32, v24, s47
	global_store_short_d16_hi v[4:5], v24, off offset:-768
	v_fmac_f32_e32 v34, v33, v18
	v_bfe_u32 v25, v33, 16, 1
	v_add3_u32 v25, v33, v25, s47
	global_store_short_d16_hi v[4:5], v25, off offset:-512
	v_fmac_f32_e32 v35, v34, v19
	v_bfe_u32 v26, v34, 16, 1
	v_add3_u32 v26, v34, v26, s47
	global_store_short_d16_hi v[4:5], v26, off offset:-256
	v_bfe_u32 v27, v35, 16, 1
	v_add3_u32 v27, v35, v27, s47
	global_store_short_d16_hi v[4:5], v27, off
	v_mov_b32_e32 v10, v35
	v_lshl_add_u64 v[4:5], v[4:5], 0, s[8:9]
	global_load_ushort v28, v[68:69], off offset:-1792
	global_load_ushort v29, v[68:69], off offset:-1536
	global_load_ushort v30, v[68:69], off offset:-1280
	global_load_ushort v31, v[68:69], off offset:-1024
	global_load_ushort v32, v[68:69], off offset:-768
	global_load_ushort v33, v[68:69], off offset:-512
	global_load_ushort v34, v[68:69], off offset:-256
	global_load_ushort v35, v[68:69], off
	v_lshl_add_u64 v[68:69], v[68:69], 0, s[8:9]
	ds_read2st64_b32 v[12:13], v0 offset0:16 offset1:18
	ds_read2st64_b32 v[14:15], v0 offset0:20 offset1:22
	ds_read2st64_b32 v[16:17], v0 offset0:24 offset1:26
	ds_read2st64_b32 v[18:19], v0 offset0:28 offset1:30
	s_waitcnt vmcnt(32)
	v_lshlrev_b32_e32 v36, 16, v36
	v_lshlrev_b32_e32 v37, 16, v37
	v_lshlrev_b32_e32 v38, 16, v38
	v_lshlrev_b32_e32 v39, 16, v39
	v_lshlrev_b32_e32 v40, 16, v40
	v_lshlrev_b32_e32 v41, 16, v41
	v_lshlrev_b32_e32 v42, 16, v42
	v_lshlrev_b32_e32 v43, 16, v43
	s_waitcnt lgkmcnt(0)
	v_fmac_f32_e32 v36, v10, v12
	v_fmac_f32_e32 v37, v36, v13
	v_bfe_u32 v20, v36, 16, 1
	v_add3_u32 v20, v36, v20, s47
	global_store_short_d16_hi v[4:5], v20, off offset:-1792
	v_fmac_f32_e32 v38, v37, v14
	v_bfe_u32 v21, v37, 16, 1
	v_add3_u32 v21, v37, v21, s47
	global_store_short_d16_hi v[4:5], v21, off offset:-1536
	v_fmac_f32_e32 v39, v38, v15
	v_bfe_u32 v22, v38, 16, 1
	v_add3_u32 v22, v38, v22, s47
	global_store_short_d16_hi v[4:5], v22, off offset:-1280
	v_fmac_f32_e32 v40, v39, v16
	v_bfe_u32 v23, v39, 16, 1
	v_add3_u32 v23, v39, v23, s47
	global_store_short_d16_hi v[4:5], v23, off offset:-1024
	v_fmac_f32_e32 v41, v40, v17
	v_bfe_u32 v24, v40, 16, 1
	v_add3_u32 v24, v40, v24, s47
	global_store_short_d16_hi v[4:5], v24, off offset:-768
	v_fmac_f32_e32 v42, v41, v18
	v_bfe_u32 v25, v41, 16, 1
	v_add3_u32 v25, v41, v25, s47
	global_store_short_d16_hi v[4:5], v25, off offset:-512
	v_fmac_f32_e32 v43, v42, v19
	v_bfe_u32 v26, v42, 16, 1
	v_add3_u32 v26, v42, v26, s47
	global_store_short_d16_hi v[4:5], v26, off offset:-256
	v_bfe_u32 v27, v43, 16, 1
	v_add3_u32 v27, v43, v27, s47
	global_store_short_d16_hi v[4:5], v27, off
	v_mov_b32_e32 v10, v43
	v_lshl_add_u64 v[4:5], v[4:5], 0, s[8:9]
	global_load_ushort v36, v[68:69], off offset:-1792
	global_load_ushort v37, v[68:69], off offset:-1536
	global_load_ushort v38, v[68:69], off offset:-1280
	global_load_ushort v39, v[68:69], off offset:-1024
	global_load_ushort v40, v[68:69], off offset:-768
	global_load_ushort v41, v[68:69], off offset:-512
	global_load_ushort v42, v[68:69], off offset:-256
	global_load_ushort v43, v[68:69], off
	v_lshl_add_u64 v[68:69], v[68:69], 0, s[8:9]
	ds_read2st64_b32 v[12:13], v0 offset0:32 offset1:34
	ds_read2st64_b32 v[14:15], v0 offset0:36 offset1:38
	ds_read2st64_b32 v[16:17], v0 offset0:40 offset1:42
	ds_read2st64_b32 v[18:19], v0 offset0:44 offset1:46
	s_waitcnt vmcnt(40)
	v_lshlrev_b32_e32 v44, 16, v44
	v_lshlrev_b32_e32 v45, 16, v45
	v_lshlrev_b32_e32 v46, 16, v46
	v_lshlrev_b32_e32 v47, 16, v47
	v_lshlrev_b32_e32 v48, 16, v48
	v_lshlrev_b32_e32 v49, 16, v49
	v_lshlrev_b32_e32 v50, 16, v50
	v_lshlrev_b32_e32 v51, 16, v51
	s_waitcnt lgkmcnt(0)
	v_fmac_f32_e32 v44, v10, v12
	v_fmac_f32_e32 v45, v44, v13
	v_bfe_u32 v20, v44, 16, 1
	v_add3_u32 v20, v44, v20, s47
	global_store_short_d16_hi v[4:5], v20, off offset:-1792
	v_fmac_f32_e32 v46, v45, v14
	v_bfe_u32 v21, v45, 16, 1
	v_add3_u32 v21, v45, v21, s47
	global_store_short_d16_hi v[4:5], v21, off offset:-1536
	v_fmac_f32_e32 v47, v46, v15
	v_bfe_u32 v22, v46, 16, 1
	v_add3_u32 v22, v46, v22, s47
	global_store_short_d16_hi v[4:5], v22, off offset:-1280
	v_fmac_f32_e32 v48, v47, v16
	v_bfe_u32 v23, v47, 16, 1
	v_add3_u32 v23, v47, v23, s47
	global_store_short_d16_hi v[4:5], v23, off offset:-1024
	v_fmac_f32_e32 v49, v48, v17
	v_bfe_u32 v24, v48, 16, 1
	v_add3_u32 v24, v48, v24, s47
	global_store_short_d16_hi v[4:5], v24, off offset:-768
	v_fmac_f32_e32 v50, v49, v18
	v_bfe_u32 v25, v49, 16, 1
	v_add3_u32 v25, v49, v25, s47
	global_store_short_d16_hi v[4:5], v25, off offset:-512
	v_fmac_f32_e32 v51, v50, v19
	v_bfe_u32 v26, v50, 16, 1
	v_add3_u32 v26, v50, v26, s47
	global_store_short_d16_hi v[4:5], v26, off offset:-256
	v_bfe_u32 v27, v51, 16, 1
	v_add3_u32 v27, v51, v27, s47
	global_store_short_d16_hi v[4:5], v27, off
	v_mov_b32_e32 v10, v51
	v_lshl_add_u64 v[4:5], v[4:5], 0, s[8:9]
	global_load_ushort v44, v[68:69], off offset:-1792
	global_load_ushort v45, v[68:69], off offset:-1536
	global_load_ushort v46, v[68:69], off offset:-1280
	global_load_ushort v47, v[68:69], off offset:-1024
	global_load_ushort v48, v[68:69], off offset:-768
	global_load_ushort v49, v[68:69], off offset:-512
	global_load_ushort v50, v[68:69], off offset:-256
	global_load_ushort v51, v[68:69], off
	v_lshl_add_u64 v[68:69], v[68:69], 0, s[8:9]
	ds_read2st64_b32 v[12:13], v0 offset0:48 offset1:50
	ds_read2st64_b32 v[14:15], v0 offset0:52 offset1:54
	ds_read2st64_b32 v[16:17], v0 offset0:56 offset1:58
	ds_read2st64_b32 v[18:19], v0 offset0:60 offset1:62
	s_waitcnt vmcnt(48)
	v_lshlrev_b32_e32 v52, 16, v52
	v_lshlrev_b32_e32 v53, 16, v53
	v_lshlrev_b32_e32 v54, 16, v54
	v_lshlrev_b32_e32 v55, 16, v55
	v_lshlrev_b32_e32 v56, 16, v56
	v_lshlrev_b32_e32 v57, 16, v57
	v_lshlrev_b32_e32 v58, 16, v58
	v_lshlrev_b32_e32 v59, 16, v59
	s_waitcnt lgkmcnt(0)
	v_fmac_f32_e32 v52, v10, v12
	v_fmac_f32_e32 v53, v52, v13
	v_bfe_u32 v20, v52, 16, 1
	v_add3_u32 v20, v52, v20, s47
	global_store_short_d16_hi v[4:5], v20, off offset:-1792
	v_fmac_f32_e32 v54, v53, v14
	v_bfe_u32 v21, v53, 16, 1
	v_add3_u32 v21, v53, v21, s47
	global_store_short_d16_hi v[4:5], v21, off offset:-1536
	v_fmac_f32_e32 v55, v54, v15
	v_bfe_u32 v22, v54, 16, 1
	v_add3_u32 v22, v54, v22, s47
	global_store_short_d16_hi v[4:5], v22, off offset:-1280
	v_fmac_f32_e32 v56, v55, v16
	v_bfe_u32 v23, v55, 16, 1
	v_add3_u32 v23, v55, v23, s47
	global_store_short_d16_hi v[4:5], v23, off offset:-1024
	v_fmac_f32_e32 v57, v56, v17
	v_bfe_u32 v24, v56, 16, 1
	v_add3_u32 v24, v56, v24, s47
	global_store_short_d16_hi v[4:5], v24, off offset:-768
	v_fmac_f32_e32 v58, v57, v18
	v_bfe_u32 v25, v57, 16, 1
	v_add3_u32 v25, v57, v25, s47
	global_store_short_d16_hi v[4:5], v25, off offset:-512
	v_fmac_f32_e32 v59, v58, v19
	v_bfe_u32 v26, v58, 16, 1
	v_add3_u32 v26, v58, v26, s47
	global_store_short_d16_hi v[4:5], v26, off offset:-256
	v_bfe_u32 v27, v59, 16, 1
	v_add3_u32 v27, v59, v27, s47
	global_store_short_d16_hi v[4:5], v27, off
	v_mov_b32_e32 v10, v59
	v_lshl_add_u64 v[4:5], v[4:5], 0, s[8:9]
	v_add_u32_e32 v0, 0x4000, v0
	s_mov_b32 s6, 7
.Lscan_loop:
	global_load_ushort v52, v[68:69], off offset:-1792
	global_load_ushort v53, v[68:69], off offset:-1536
	global_load_ushort v54, v[68:69], off offset:-1280
	global_load_ushort v55, v[68:69], off offset:-1024
	global_load_ushort v56, v[68:69], off offset:-768
	global_load_ushort v57, v[68:69], off offset:-512
	global_load_ushort v58, v[68:69], off offset:-256
	global_load_ushort v59, v[68:69], off
	v_lshl_add_u64 v[68:69], v[68:69], 0, s[8:9]
	ds_read2st64_b32 v[12:13], v0 offset0:0 offset1:2
	ds_read2st64_b32 v[14:15], v0 offset0:4 offset1:6
	ds_read2st64_b32 v[16:17], v0 offset0:8 offset1:10
	ds_read2st64_b32 v[18:19], v0 offset0:12 offset1:14
	s_waitcnt vmcnt(48)
	v_lshlrev_b32_e32 v28, 16, v28
	v_lshlrev_b32_e32 v29, 16, v29
	v_lshlrev_b32_e32 v30, 16, v30
	v_lshlrev_b32_e32 v31, 16, v31
	v_lshlrev_b32_e32 v32, 16, v32
	v_lshlrev_b32_e32 v33, 16, v33
	v_lshlrev_b32_e32 v34, 16, v34
	v_lshlrev_b32_e32 v35, 16, v35
	s_waitcnt lgkmcnt(0)
	v_fmac_f32_e32 v28, v10, v12
	v_fmac_f32_e32 v29, v28, v13
	v_bfe_u32 v20, v28, 16, 1
	v_add3_u32 v20, v28, v20, s47
	global_store_short_d16_hi v[4:5], v20, off offset:-1792
	v_fmac_f32_e32 v30, v29, v14
	v_bfe_u32 v21, v29, 16, 1
	v_add3_u32 v21, v29, v21, s47
	global_store_short_d16_hi v[4:5], v21, off offset:-1536
	v_fmac_f32_e32 v31, v30, v15
	v_bfe_u32 v22, v30, 16, 1
	v_add3_u32 v22, v30, v22, s47
	global_store_short_d16_hi v[4:5], v22, off offset:-1280
	v_fmac_f32_e32 v32, v31, v16
	v_bfe_u32 v23, v31, 16, 1
	v_add3_u32 v23, v31, v23, s47
	global_store_short_d16_hi v[4:5], v23, off offset:-1024
	v_fmac_f32_e32 v33, v32, v17
	v_bfe_u32 v24, v32, 16, 1
	v_add3_u32 v24, v32, v24, s47
	global_store_short_d16_hi v[4:5], v24, off offset:-768
	v_fmac_f32_e32 v34, v33, v18
	v_bfe_u32 v25, v33, 16, 1
	v_add3_u32 v25, v33, v25, s47
	global_store_short_d16_hi v[4:5], v25, off offset:-512
	v_fmac_f32_e32 v35, v34, v19
	v_bfe_u32 v26, v34, 16, 1
	v_add3_u32 v26, v34, v26, s47
	global_store_short_d16_hi v[4:5], v26, off offset:-256
	v_bfe_u32 v27, v35, 16, 1
	v_add3_u32 v27, v35, v27, s47
	global_store_short_d16_hi v[4:5], v27, off
	v_mov_b32_e32 v10, v35
	v_lshl_add_u64 v[4:5], v[4:5], 0, s[8:9]
	global_load_ushort v28, v[68:69], off offset:-1792
	global_load_ushort v29, v[68:69], off offset:-1536
	global_load_ushort v30, v[68:69], off offset:-1280
	global_load_ushort v31, v[68:69], off offset:-1024
	global_load_ushort v32, v[68:69], off offset:-768
	global_load_ushort v33, v[68:69], off offset:-512
	global_load_ushort v34, v[68:69], off offset:-256
	global_load_ushort v35, v[68:69], off
	v_lshl_add_u64 v[68:69], v[68:69], 0, s[8:9]
	ds_read2st64_b32 v[12:13], v0 offset0:16 offset1:18
	ds_read2st64_b32 v[14:15], v0 offset0:20 offset1:22
	ds_read2st64_b32 v[16:17], v0 offset0:24 offset1:26
	ds_read2st64_b32 v[18:19], v0 offset0:28 offset1:30
	s_waitcnt vmcnt(48)
	v_lshlrev_b32_e32 v36, 16, v36
	v_lshlrev_b32_e32 v37, 16, v37
	v_lshlrev_b32_e32 v38, 16, v38
	v_lshlrev_b32_e32 v39, 16, v39
	v_lshlrev_b32_e32 v40, 16, v40
	v_lshlrev_b32_e32 v41, 16, v41
	v_lshlrev_b32_e32 v42, 16, v42
	v_lshlrev_b32_e32 v43, 16, v43
	s_waitcnt lgkmcnt(0)
	v_fmac_f32_e32 v36, v10, v12
	v_fmac_f32_e32 v37, v36, v13
	v_bfe_u32 v20, v36, 16, 1
	v_add3_u32 v20, v36, v20, s47
	global_store_short_d16_hi v[4:5], v20, off offset:-1792
	v_fmac_f32_e32 v38, v37, v14
	v_bfe_u32 v21, v37, 16, 1
	v_add3_u32 v21, v37, v21, s47
	global_store_short_d16_hi v[4:5], v21, off offset:-1536
	v_fmac_f32_e32 v39, v38, v15
	v_bfe_u32 v22, v38, 16, 1
	v_add3_u32 v22, v38, v22, s47
	global_store_short_d16_hi v[4:5], v22, off offset:-1280
	v_fmac_f32_e32 v40, v39, v16
	v_bfe_u32 v23, v39, 16, 1
	v_add3_u32 v23, v39, v23, s47
	global_store_short_d16_hi v[4:5], v23, off offset:-1024
	v_fmac_f32_e32 v41, v40, v17
	v_bfe_u32 v24, v40, 16, 1
	v_add3_u32 v24, v40, v24, s47
	global_store_short_d16_hi v[4:5], v24, off offset:-768
	v_fmac_f32_e32 v42, v41, v18
	v_bfe_u32 v25, v41, 16, 1
	v_add3_u32 v25, v41, v25, s47
	global_store_short_d16_hi v[4:5], v25, off offset:-512
	v_fmac_f32_e32 v43, v42, v19
	v_bfe_u32 v26, v42, 16, 1
	v_add3_u32 v26, v42, v26, s47
	global_store_short_d16_hi v[4:5], v26, off offset:-256
	v_bfe_u32 v27, v43, 16, 1
	v_add3_u32 v27, v43, v27, s47
	global_store_short_d16_hi v[4:5], v27, off
	v_mov_b32_e32 v10, v43
	v_lshl_add_u64 v[4:5], v[4:5], 0, s[8:9]
	global_load_ushort v36, v[68:69], off offset:-1792
	global_load_ushort v37, v[68:69], off offset:-1536
	global_load_ushort v38, v[68:69], off offset:-1280
	global_load_ushort v39, v[68:69], off offset:-1024
	global_load_ushort v40, v[68:69], off offset:-768
	global_load_ushort v41, v[68:69], off offset:-512
	global_load_ushort v42, v[68:69], off offset:-256
	global_load_ushort v43, v[68:69], off
	v_lshl_add_u64 v[68:69], v[68:69], 0, s[8:9]
	ds_read2st64_b32 v[12:13], v0 offset0:32 offset1:34
	ds_read2st64_b32 v[14:15], v0 offset0:36 offset1:38
	ds_read2st64_b32 v[16:17], v0 offset0:40 offset1:42
	ds_read2st64_b32 v[18:19], v0 offset0:44 offset1:46
	s_waitcnt vmcnt(48)
	v_lshlrev_b32_e32 v44, 16, v44
	v_lshlrev_b32_e32 v45, 16, v45
	v_lshlrev_b32_e32 v46, 16, v46
	v_lshlrev_b32_e32 v47, 16, v47
	v_lshlrev_b32_e32 v48, 16, v48
	v_lshlrev_b32_e32 v49, 16, v49
	v_lshlrev_b32_e32 v50, 16, v50
	v_lshlrev_b32_e32 v51, 16, v51
	s_waitcnt lgkmcnt(0)
	v_fmac_f32_e32 v44, v10, v12
	v_fmac_f32_e32 v45, v44, v13
	v_bfe_u32 v20, v44, 16, 1
	v_add3_u32 v20, v44, v20, s47
	global_store_short_d16_hi v[4:5], v20, off offset:-1792
	v_fmac_f32_e32 v46, v45, v14
	v_bfe_u32 v21, v45, 16, 1
	v_add3_u32 v21, v45, v21, s47
	global_store_short_d16_hi v[4:5], v21, off offset:-1536
	v_fmac_f32_e32 v47, v46, v15
	v_bfe_u32 v22, v46, 16, 1
	v_add3_u32 v22, v46, v22, s47
	global_store_short_d16_hi v[4:5], v22, off offset:-1280
	v_fmac_f32_e32 v48, v47, v16
	v_bfe_u32 v23, v47, 16, 1
	v_add3_u32 v23, v47, v23, s47
	global_store_short_d16_hi v[4:5], v23, off offset:-1024
	v_fmac_f32_e32 v49, v48, v17
	v_bfe_u32 v24, v48, 16, 1
	v_add3_u32 v24, v48, v24, s47
	global_store_short_d16_hi v[4:5], v24, off offset:-768
	v_fmac_f32_e32 v50, v49, v18
	v_bfe_u32 v25, v49, 16, 1
	v_add3_u32 v25, v49, v25, s47
	global_store_short_d16_hi v[4:5], v25, off offset:-512
	v_fmac_f32_e32 v51, v50, v19
	v_bfe_u32 v26, v50, 16, 1
	v_add3_u32 v26, v50, v26, s47
	global_store_short_d16_hi v[4:5], v26, off offset:-256
	v_bfe_u32 v27, v51, 16, 1
	v_add3_u32 v27, v51, v27, s47
	global_store_short_d16_hi v[4:5], v27, off
	v_mov_b32_e32 v10, v51
	v_lshl_add_u64 v[4:5], v[4:5], 0, s[8:9]
	global_load_ushort v44, v[68:69], off offset:-1792
	global_load_ushort v45, v[68:69], off offset:-1536
	global_load_ushort v46, v[68:69], off offset:-1280
	global_load_ushort v47, v[68:69], off offset:-1024
	global_load_ushort v48, v[68:69], off offset:-768
	global_load_ushort v49, v[68:69], off offset:-512
	global_load_ushort v50, v[68:69], off offset:-256
	global_load_ushort v51, v[68:69], off
	v_lshl_add_u64 v[68:69], v[68:69], 0, s[8:9]
	ds_read2st64_b32 v[12:13], v0 offset0:48 offset1:50
	ds_read2st64_b32 v[14:15], v0 offset0:52 offset1:54
	ds_read2st64_b32 v[16:17], v0 offset0:56 offset1:58
	ds_read2st64_b32 v[18:19], v0 offset0:60 offset1:62
	s_waitcnt vmcnt(48)
	v_lshlrev_b32_e32 v52, 16, v52
	v_lshlrev_b32_e32 v53, 16, v53
	v_lshlrev_b32_e32 v54, 16, v54
	v_lshlrev_b32_e32 v55, 16, v55
	v_lshlrev_b32_e32 v56, 16, v56
	v_lshlrev_b32_e32 v57, 16, v57
	v_lshlrev_b32_e32 v58, 16, v58
	v_lshlrev_b32_e32 v59, 16, v59
	s_waitcnt lgkmcnt(0)
	v_fmac_f32_e32 v52, v10, v12
	v_fmac_f32_e32 v53, v52, v13
	v_bfe_u32 v20, v52, 16, 1
	v_add3_u32 v20, v52, v20, s47
	global_store_short_d16_hi v[4:5], v20, off offset:-1792
	v_fmac_f32_e32 v54, v53, v14
	v_bfe_u32 v21, v53, 16, 1
	v_add3_u32 v21, v53, v21, s47
	global_store_short_d16_hi v[4:5], v21, off offset:-1536
	v_fmac_f32_e32 v55, v54, v15
	v_bfe_u32 v22, v54, 16, 1
	v_add3_u32 v22, v54, v22, s47
	global_store_short_d16_hi v[4:5], v22, off offset:-1280
	v_fmac_f32_e32 v56, v55, v16
	v_bfe_u32 v23, v55, 16, 1
	v_add3_u32 v23, v55, v23, s47
	global_store_short_d16_hi v[4:5], v23, off offset:-1024
	v_fmac_f32_e32 v57, v56, v17
	v_bfe_u32 v24, v56, 16, 1
	v_add3_u32 v24, v56, v24, s47
	global_store_short_d16_hi v[4:5], v24, off offset:-768
	v_fmac_f32_e32 v58, v57, v18
	v_bfe_u32 v25, v57, 16, 1
	v_add3_u32 v25, v57, v25, s47
	global_store_short_d16_hi v[4:5], v25, off offset:-512
	v_fmac_f32_e32 v59, v58, v19
	v_bfe_u32 v26, v58, 16, 1
	v_add3_u32 v26, v58, v26, s47
	global_store_short_d16_hi v[4:5], v26, off offset:-256
	v_bfe_u32 v27, v59, 16, 1
	v_add3_u32 v27, v59, v27, s47
	global_store_short_d16_hi v[4:5], v27, off
	v_mov_b32_e32 v10, v59
	v_lshl_add_u64 v[4:5], v[4:5], 0, s[8:9]
	v_add_u32_e32 v0, 0x4000, v0
	s_add_i32 s6, s6, -1
	s_cmp_lg_u32 s6, 0
	s_cbranch_scc1 .Lscan_loop
	s_add_i32 s26, s26, s80
	s_cmp_gt_i32 s26, 0x1ffff
	s_cbranch_scc0 .LBB0_461
